# static s_setprio 1 for waves 4-7 over the whole layer loop, per-segment GEMM toggles removed
# baseline (speedup 1.0000x reference)
; __global__ void __launch_bounds__(512, 2) hybrid_fwd(Args unused_args) {
;     ...
;     for (int l = 0; l < 2; ++l) {
; for (int rep_ = 0; rep_ < REP_GEMM; ++rep_) {
;     ...
;         { PH_LOCALS
;           pg8::Gemm g{XB, (const bf16_t*)(wb + W_IN), T, HP, 1024, 1024}; pg8::StaticOrder S; S.init(T, HP, G, bid);
;           EpiIn E{Hh, (float*)(ws + WS_DT), (float*)(ws + WS_SSQQ), (float*)(ws + WS_SSQKV)};
;           pg8::gemm_phase<EpiIn, pg8::StaticOrder, true, true>(lds, g, S, E, wv0); }
.LBB0_652:
	s_cmp_ge_u32 s77, 4
	s_cbranch_scc0 .Lmy_lprio_skip
	s_setprio 1
